# phase-1 (input GEMM) start staggered: workgroups 152..255 (11 units, no sample unit) sleep ~17us first so epilogue store bursts of the two cohorts do not coincide
# baseline (speedup 1.0000x reference)
; __global__ void __launch_bounds__(512, 2) fwd_megakernel(Args ka) {
;     ...
;             int ph = -1, g = 0;
;             if (w == 0) { if (step <= 9) { ph = step; g = 1; } else if (step <= 17) { ph = step - 9; g = 2; } else { ph = 9; g = 2; } }
;             else if (w == 1) { if (step == 9) { ph = 0; g = 2; } }
;             else { if (step <= 4) ph = step; else if (step == 5) ph = 10; else if (step <= 10) ph = step - 1; g = 0; }
;             ph = __builtin_amdgcn_readfirstlane(ph); g = __builtin_amdgcn_readfirstlane(g);
;             if (ph < 0) continue;
;             switch (ph) {
;             case 0: { PH_BEGIN rms_rows_bf16(G.x, G.XN, a.in[7], G.nvalid, M, gw, ngw, lane, G.SSQ); } break;
;             case 1: { PH_BEGIN EpiIn E{G.QD, G.KD, G.VD, G.GD, G.GM, G.ZS, G.okd, G.ovd, G.nvalid, 0.125f * LOG2E};
;                       run_gemm(lds, G.XN, (const bf16*)(ws + WS_WIN), M, NIN, 1024, E, tid_, 0, g == 0 ? 128 : 0); } break;
.LBB0_186:
	v_readfirstlane_b32 s0, v0
	s_cmp_lt_i32 s0, 0
	s_cbranch_scc1 .LBB0_180
	v_writelane_b32 v247, s0, 63
	v_readlane_b32 s98, v247, 61
	s_cmp_eq_u32 s98, 0
	s_cbranch_scc1 .Lstg_done
	v_readlane_b32 s98, v247, 35
	s_cmp_lg_u32 s0, 1
	s_cbranch_scc1 .Lstg_next0
	s_cmp_lt_u32 s98, 152
	s_cbranch_scc1 .Lstg_done
	s_sleep 127
	s_sleep 127
	s_sleep 127
	s_sleep 127
	s_branch .Lstg_done
.Lstg_next0:
.Lstg_done:
	s_cmp_lt_i32 s0, 5
	s_mov_b64 s[0:1], -1
	s_cbranch_scc1 .LBB0_498
	v_readlane_b32 s0, v247, 63
	s_cmp_lt_i32 s0, 7
	s_mov_b64 s[0:1], -1
	s_cbranch_scc1 .LBB0_348
	v_readlane_b32 s0, v247, 63
	s_cmp_lt_i32 s0, 8
	s_mov_b64 s[0:1], -1
	s_cbranch_scc1 .LBB0_311
	v_readlane_b32 s0, v247, 63
	s_cmp_lt_i32 s0, 9
	s_mov_b64 s[0:1], -1
	s_cbranch_scc1 .LBB0_207
	v_readlane_b32 s0, v247, 63
	s_cmp_lg_u32 s0, 9
	s_mov_b64 s[0:1], -1
	s_cbranch_scc0 .LBB0_200
	v_readlane_b32 s2, v247, 61
	s_mov_b32 s0, s84
	s_mov_b32 s5, s2
	s_mov_b32 s1, s67
	v_readlane_b32 s3, v247, 62
	v_mbcnt_lo_u32_b32 v0, -1, s1
	v_mbcnt_hi_u32_b32 v0, -1, v0
	s_mov_b32 s1, s67
	s_add_i32 s1, s1, 0
	s_add_i32 s1, s1, 0x20000
	v_mov_b32_e32 v1, s1
	ds_read2_b64 v[2:5], v1 offset0:13 offset1:27
	s_add_i32 s4, s0, s81
	s_cmpk_gt_i32 s4, 0xbff
	s_waitcnt lgkmcnt(0)
	v_readfirstlane_b32 s1, v3
	v_readfirstlane_b32 s0, v2
	v_readfirstlane_b32 s3, v5
	v_readfirstlane_b32 s2, v4
	s_cbranch_scc1 .LBB0_199
	s_nop 3
	global_load_dword v10, v204, s[2:3] offset:2048
	s_cmp_eq_u32 s5, 0
	s_mov_b32 s5, 0x2500000
	s_cselect_b32 s5, s5, 0x3a00000
	s_mov_b32 s6, 0x180000
	s_mov_b32 s7, 0x480000
	s_cselect_b32 s6, s6, 0xc000000
	s_cselect_b32 s7, s7, 0x24000000
	s_add_u32 s8, s2, s5
	s_addc_u32 s9, s3, 0
	s_add_u32 s5, s8, s6
	s_addc_u32 s6, s9, 0
	s_add_u32 s7, s8, s7
	s_addc_u32 s8, s9, 0
	s_add_u32 s9, s2, 0x3800000
	s_addc_u32 s10, s3, 0
	v_ashrrev_i32_e32 v1, 31, v0
	s_add_u32 s11, s2, 0x3820000
	v_lshlrev_b64 v[6:7], 2, v[0:1]
	s_addc_u32 s12, s3, 0
	v_lshl_add_u64 v[4:5], s[2:3], 0, v[6:7]
	s_mov_b64 s[2:3], 0x3400000
	v_lshl_add_u64 v[2:3], v[4:5], 0, s[2:3]
	s_mov_b64 s[2:3], 0x2c00000
	v_lshl_add_u64 v[4:5], v[4:5], 0, s[2:3]
	v_lshl_add_u64 v[6:7], s[0:1], 0, v[6:7]
	s_branch .LBB0_195
